# no grid barrier between phase 0 and phase 1: the 32 workgroups that produce the layer-0 mixer shift/scale publish on a counter, every workgroup acquires before the modulate pass
# baseline (speedup 1.0000x reference)
.LBB0_10:
	s_cmp_eq_u32 s54, 12
	v_readlane_b32 s2, v252, 12
	v_mov_b32_e32 v188, v191
	s_cselect_b64 s[0:1], -1, 0
	v_readlane_b32 s3, v252, 13
	v_readlane_b32 s42, v252, 0
	v_ashrrev_i32_e32 v190, 6, v188
	s_and_b64 s[0:1], s[2:3], s[0:1]
	v_readfirstlane_b32 s8, v190
	v_readlane_b32 s43, v252, 1
	s_and_b64 vcc, exec, s[0:1]
	s_cbranch_vccnz .LBB0_28
	s_load_dwordx4 s[12:15], s[42:43], 0x88
	v_readlane_b32 s0, v253, 42
	s_add_i32 s0, s8, s0
	v_and_b32_e32 v223, 63, v188
	v_writelane_b32 v254, s0, 0
	s_waitcnt lgkmcnt(0)
	s_add_u32 s2, s14, 0x3300000
	s_addc_u32 s3, s15, 0
	v_writelane_b32 v254, s1, 1
	s_add_u32 s0, s14, 0x100000
	s_addc_u32 s1, s15, 0
	v_writelane_b32 v254, s0, 2
	s_mov_b64 s[6:7], -1
	s_mov_b64 s[4:5], 0
	v_writelane_b32 v254, s1, 3
	s_add_u32 s0, s14, 0x128000
	s_addc_u32 s1, s15, 0
	v_writelane_b32 v254, s0, 4
	s_nop 1
	v_writelane_b32 v254, s1, 5
	s_add_u32 s0, s14, 0x12a000
	s_addc_u32 s1, s15, 0
	v_writelane_b32 v254, s0, 6
	s_nop 1
	v_writelane_b32 v254, s1, 7
	s_add_u32 s0, s14, 0x3500000
	v_writelane_b32 v254, s12, 8
	s_addc_u32 s1, s15, 0
	s_cmp_lt_i32 s54, 1
	v_writelane_b32 v254, s13, 9
	v_writelane_b32 v254, s14, 10
	v_writelane_b32 v254, s15, 11
	v_writelane_b32 v254, s0, 12
	s_nop 1
	v_writelane_b32 v254, s1, 13
	s_mov_b64 s[0:1], 0
	v_writelane_b32 v254, s8, 14
	s_cbranch_scc1 .LBB0_31
	s_cmp_eq_u32 s54, 1
	s_mov_b64 s[4:5], -1
	s_cbranch_scc0 .LBB0_30
	v_readlane_b32 s4, v254, 0
	s_cmpk_gt_i32 s4, 0x41ff
	v_readlane_b32 s5, v254, 1
	s_cbranch_scc1 .LBB0_29
	v_readfirstlane_b32 s4, v191
	s_nop 3
	s_cmp_lt_u32 s4, 64
	s_cbranch_scc0 .Lpa_acq_bar
	v_readlane_b32 s4, v254, 10
	v_readlane_b32 s5, v254, 11
	s_nop 3
	s_add_u32 s4, s4, 0x16a00
	s_addc_u32 s5, s5, 0
	s_mov_b32 s8, 0
.Lpa_spin:
	global_load_dword v2, v1, s[4:5] sc1
	s_waitcnt vmcnt(0)
	v_readfirstlane_b32 s9, v2
	s_nop 3
	s_cmp_ge_u32 s9, 32
	s_cbranch_scc1 .Lpa_got
	s_sleep 2
	s_add_u32 s8, s8, 1
	s_cmp_lt_u32 s8, 0x4000
	s_cbranch_scc1 .Lpa_spin

.Lpa_acq_bar:
	s_barrier
	v_readlane_b32 s4, v254, 12
	v_lshlrev_b32_e32 v0, 3, v223
	v_readlane_b32 s5, v254, 13
	v_lshlrev_b32_e32 v2, 2, v223
	v_or_b32_e32 v4, 0x100, v2
	v_lshl_add_u64 v[6:7], s[4:5], 0, v[0:1]
	v_readlane_b32 s4, v254, 0
	s_mov_b32 s8, s4
	s_mov_b32 s6, s8
	v_or_b32_e32 v8, 0x200, v2
	v_or_b32_e32 v10, 0x300, v2
	v_readlane_b32 s5, v254, 1
	s_ashr_i32 s9, s4, 31
	v_writelane_b32 v254, s6, 0
	s_lshl_b64 s[4:5], s[8:9], 12
	v_lshlrev_b32_e32 v0, 2, v2
	v_lshlrev_b32_e32 v14, 2, v4
	v_lshlrev_b32_e32 v15, 2, v8
	v_lshlrev_b32_e32 v16, 2, v10
	v_writelane_b32 v254, s7, 1
	s_mov_b64 s[6:7], s[8:9]
	s_load_dwordx2 s[98:99], s[42:43], 0x0
	s_waitcnt lgkmcnt(0)
	s_branch .LBB0_16

.LBB0_1362:
	s_cmpk_lt_i32 s78, 32
	s_cbranch_scc0 .Lp0_nopub
	s_waitcnt vmcnt(0)
	s_barrier
	v_readfirstlane_b32 s0, v191
	s_nop 3
	s_cmp_ge_u32 s0, 64
	s_cbranch_scc1 .Lp0_nopub
	v_readlane_b32 s0, v254, 10
	v_readlane_b32 s1, v254, 11
	s_nop 3
	s_add_u32 s0, s0, 0x16a00
	s_addc_u32 s1, s1, 0
	s_mov_b64 vcc, exec
	s_mov_b64 exec, 1
	buffer_wbl2 sc1
	s_waitcnt vmcnt(0)
	global_atomic_add v1, v220, s[0:1]
	s_mov_b64 exec, vcc

.Ll4_b:
	s_add_i32 s54, s54, 1
	s_cmp_eq_u32 s54, 15
	s_cselect_b32 s54, s55, s54
	v_readlane_b32 s26, v254, 21
	v_readlane_b32 s36, v254, 25
	v_readlane_b32 s40, v254, 29
	s_cmp_ge_i32 s54, s55
	v_readlane_b32 s27, v254, 22
	v_readlane_b32 s37, v254, 26
	v_readlane_b32 s41, v254, 30
	s_cbranch_scc1 .Lskip_seam
	v_readlane_b32 s0, v255, 61
	s_nop 3
	s_cmp_eq_u32 s0, 1
	s_cbranch_scc1 .LBB0_1379
	s_cmp_eq_u32 s54, 1
	s_cbranch_scc1 .Lskip_seam
	s_cmp_eq_u32 s54, 6
	s_cbranch_scc1 .Lskip_seam
	s_cmp_eq_u32 s54, 9
	s_cbranch_scc0 .LBB0_1379
